# static wave priority raise (s_setprio 2) for the DSA gathered-attention part of an item, back to 0 at its end
# baseline (speedup 1.0000x reference)
; __device__ __forceinline__ void dsa_item(const KP& p, int b, int tile, char* smem) {
;     ...
;   for (int jr = 0; jr < 4 * DSA_ATT_REP; ++jr) {
;     const int j = jr & 3;
;     const int tk = wid * 4 + j;
;     const int t = t0 + tk;
;     const int nsel = min(cnt[tk], 256);
;     const half_t* urow = ub + (size_t)t * NU;
;     const int col = lane & 15;
;     h8 q0, q1;
; #pragma unroll
;     for (int e = 0; e < 8; ++e) { q0[e] = (half_t)0.f; q1[e] = (half_t)0.f; }
;     if (col < 8) {
;       q0 = *(const h8*)(urow + C_BQ + col * 64 + hq * 8);
;       q1 = *(const h8*)(urow + C_BQ + col * 64 + 32 + hq * 8);
;     }
;     ...
;       const bool b2 = (rs & 4) != 0, b1 = (rs & 2) != 0, b0 = (rs & 1) != 0;
.LBB0_1423:
	s_setprio 2
	v_mov_b32_e32 v250, v224
	v_and_b32_e32 v4, 64, v237
	v_xor_b32_e32 v0, 16, v237
	v_add_u32_e32 v2, 64, v4
	v_cmp_lt_i32_e32 vcc, v0, v2
	v_and_b32_e32 v5, 7, v129
	v_lshrrev_b32_e32 v165, 3, v131
	v_cndmask_b32_e32 v0, v237, v0, vcc
	v_lshlrev_b32_e32 v161, 2, v0
	v_xor_b32_e32 v0, 32, v237
	v_cmp_lt_i32_e32 vcc, v0, v2
	v_readlane_b32 s2, v252, 45
	v_readlane_b32 s3, v252, 46
	v_cndmask_b32_e32 v0, v237, v0, vcc
	v_lshlrev_b32_e32 v162, 2, v0
	v_or_b32_e32 v0, v4, v5
	v_lshlrev_b32_e32 v163, 2, v0
	v_xor_b32_e32 v0, 8, v237
	v_cmp_lt_i32_e32 vcc, v0, v2
	v_lshlrev_b32_e32 v3, 13, v135
	v_lshlrev_b32_e32 v2, 3, v5
	v_cndmask_b32_e32 v0, v237, v0, vcc
	v_lshlrev_b32_e32 v164, 2, v0
	v_and_b32_e32 v0, 32, v129
	v_cmp_eq_u32_e64 s[40:41], 0, v0
	v_and_b32_e32 v0, 16, v129
	v_cmp_eq_u32_e64 s[42:43], 0, v0
	v_and_b32_e32 v0, 8, v129
	v_cmp_eq_u32_e64 s[44:45], 0, v0
	v_or_b32_e32 v0, v4, v165
	v_lshlrev_b32_e32 v166, 2, v0
	v_lshlrev_b32_e32 v0, 7, v165
	v_lshl_add_u64 v[8:9], s[2:3], 0, v[0:1]
	v_lshlrev_b32_e32 v0, 4, v5
	s_waitcnt vmcnt(0)
	v_lshl_add_u64 v[82:83], v[8:9], 0, v[0:1]
	v_lshlrev_b32_e32 v0, 1, v165
	v_lshlrev_b32_e32 v4, 6, v165
	v_lshlrev_b32_e32 v6, 6, v157
	v_and_b32_e32 v7, 56, v129
	v_lshl_or_b32 v0, v135, 11, v0
	v_cmp_gt_u32_e64 s[38:39], 8, v157
	s_mov_b32 s8, 0
	v_lshl_or_b32 v167, v157, 2, v3
	v_lshl_or_b32 v168, v131, 2, v3
	v_lshl_or_b32 v169, v7, 2, v3
	v_add_u32_e32 v170, 0x8000, v0
	v_lshlrev_b32_e32 v84, 1, v6
	v_lshlrev_b32_e32 v0, 1, v2
	v_lshlrev_b32_e32 v86, 1, v4
	s_branch .LBB0_1425

; __device__ __forceinline__ void dsa_item(const KP& p, int b, int tile, char* smem) {
;     ...
;     __builtin_amdgcn_wave_barrier();
;   }
;   __syncthreads();
; }
.LBB0_1529:
	s_setprio 0
	v_mov_b32_e32 v224, v250
	v_mov_b32_e32 v225, 0x11ff0
	v_mov_b32_e32 v226, 1
	v_mov_b32_e32 v227, 0x11fe0
	v_mov_b32_e32 v228, 0x11fe4
	v_mov_b32_e32 v229, 0x100
	v_mov_b32_e32 v230, 2
	v_mov_b32_e32 v231, 0x3727c5ac
	v_mov_b32_e32 v232, 0x11fa0
	v_mov_b32_e32 v233, 0x80000
	v_mov_b32_e32 v234, 0x1d0000
	v_mov_b32_e32 v235, 0xa800
	s_barrier
	s_cbranch_execnz .LBB0_604
	s_branch .LBB0_810
